# ffn1 GEMM main loop rewritten: LDS-DMA 3-stage ring, swizzled LDS, 1 barrier per K-slice, LDS-transposed epilogue with v_cvt_pk_bf16_f32
# speedup vs baseline: 1.0287x; 1.0287x over previous
.LBB0_34:
	s_andn2_b64 vcc, exec, s[36:37]
	v_writelane_b32 v235, s61, 55
	s_cbranch_vccnz .LBB0_764
	s_add_i32 s30, s64, -1
	s_mul_hi_i32 s31, s30, 0x66666667
	s_lshr_b32 s35, s31, 31
	s_ashr_i32 s31, s31, 2
	s_add_i32 s36, s31, s35
	s_mul_i32 s31, s36, 10
	s_sub_i32 s5, s30, s31
	s_lshl_b32 s30, s64, 5
	s_ashr_i32 s31, s30, 31
	s_lshl_b64 s[30:31], s[30:31], 2
	v_readlane_b32 s4, v237, 59
	s_add_u32 s6, s4, s30
	v_readlane_b32 s4, v237, 60
	s_addc_u32 s7, s4, s31
	s_add_i32 s30, s64, 8
	v_writelane_b32 v235, s6, 56
	s_cmp_lt_u32 s30, 19
	s_cselect_b32 s17, s69, s95
	v_writelane_b32 v235, s7, 57
	s_cselect_b32 s16, s68, s94
	s_cselect_b32 s31, s71, s67
	s_cselect_b32 s30, s70, s66
	s_lshl_b32 s6, s36, 10
	s_ashr_i32 s7, s6, 31
	v_writelane_b32 v235, s6, 58
	s_mul_i32 s4, s36, 3
	s_ashr_i32 s37, s36, 31
	v_writelane_b32 v235, s7, 59
	s_lshl_b32 s6, s36, 8
	v_writelane_b32 v235, s4, 60
	s_ashr_i32 s7, s6, 31
	v_writelane_b32 v235, s6, 61
	s_cmp_eq_u32 s5, 8
	s_cbranch_scc1 .Lgm_f1_entry
	s_cmp_lt_i32 s5, 4
	s_mov_b64 s[38:39], -1
	v_writelane_b32 v235, s7, 62
	v_writelane_b32 v235, s5, 63
	s_cbranch_scc1 .LBB0_561
	s_mul_i32 s38, s36, 0x12000
	v_readlane_b32 s4, v236, 3
	s_mul_hi_i32 s35, s36, 0x12000
	v_readlane_b32 s5, v236, 4
	s_add_u32 s54, s4, s38
	s_addc_u32 s55, s5, s35
	s_add_i32 s56, s61, 0xff
	v_readlane_b32 s4, v235, 63
	s_cmp_lt_i32 s4, 7
	s_mov_b64 s[38:39], -1
	s_cbranch_scc1 .LBB0_192
	v_readlane_b32 s4, v235, 63
	s_cmp_lt_i32 s4, 8
	s_cbranch_scc1 .LBB0_182
	s_lshl_b64 s[44:45], s[36:37], 23
	v_readlane_b32 s4, v235, 63
	s_cmp_lt_i32 s4, 9
	s_cbranch_scc1 .LBB0_158
	v_readlane_b32 s4, v235, 63
	s_cmp_eq_u32 s4, 9
	s_cbranch_scc0 .LBB0_157
	v_mov_b32_e32 v48, v206
	s_cmpk_gt_i32 s63, 0xff
	s_cbranch_scc1 .LBB0_157
	v_readlane_b32 s4, v236, 7
	s_add_u32 s40, s4, s44
	v_readlane_b32 s4, v236, 8
	s_addc_u32 s41, s4, s45
	s_abs_i32 s35, s61
	v_cvt_f32_u32_e32 v0, s35
	s_sub_i32 s42, 0, s35
	s_sub_i32 s38, s56, s63
	s_xor_b32 s39, s38, s61
	v_rcp_iflag_f32_e32 v0, v0
	s_abs_i32 s38, s38
	s_ashr_i32 s39, s39, 31
	v_ashrrev_i32_e32 v3, 3, v48
	v_mul_f32_e32 v0, 0x4f7ffffe, v0
	v_cvt_u32_f32_e32 v0, v0
	v_readlane_b32 s4, v236, 17
	s_waitcnt vmcnt(2)
	v_lshlrev_b32_e32 v4, 3, v48
	v_readlane_b32 s5, v236, 18
	v_readfirstlane_b32 s43, v0
	s_mul_i32 s42, s42, s43
	s_mul_hi_u32 s42, s43, s42
	s_add_i32 s43, s43, s42
	s_mul_hi_u32 s42, s38, s43
	s_mul_i32 s43, s42, s35
	s_sub_i32 s38, s38, s43
	s_add_i32 s46, s42, 1
	s_sub_i32 s43, s38, s35
	s_cmp_ge_u32 s38, s35
	s_cselect_b32 s42, s46, s42
	s_cselect_b32 s38, s43, s38
	s_add_i32 s43, s42, 1
	s_cmp_ge_u32 s38, s35
	s_cselect_b32 s35, s43, s42
	s_and_b32 s38, s63, 31
	s_mulk_i32 s38, 0xc0
	v_add_u32_e32 v0, s38, v3
	v_ashrrev_i32_e32 v1, 31, v0
	v_lshlrev_b64 v[0:1], 13, v[0:1]
	v_and_b32_e32 v4, 56, v4
	s_lshl_b32 s38, s63, 2
	v_lshl_add_u64 v[0:1], s[4:5], 0, v[0:1]
	v_lshlrev_b32_e32 v44, 1, v4
	v_mov_b32_e32 v45, v2
	s_and_b32 s38, s38, 0xffffff80
	v_lshl_add_u64 v[46:47], v[0:1], 0, v[44:45]
	v_add_u32_e32 v0, s38, v3
	s_mov_b32 s4, 0x80000
	v_ashrrev_i32_e32 v1, 31, v0
	v_add_co_u32_e32 v4, vcc, s4, v46
	v_lshlrev_b64 v[0:1], 13, v[0:1]
	s_nop 0
	v_addc_co_u32_e32 v5, vcc, 0, v47, vcc
	v_lshl_add_u64 v[0:1], s[40:41], 0, v[0:1]
	v_add_co_u32_e32 v8, vcc, 0x100000, v46
	v_lshl_add_u64 v[0:1], v[0:1], 0, v[44:45]
	s_nop 0
	v_addc_co_u32_e32 v9, vcc, 0, v47, vcc
	global_load_dwordx4 v[4:7], v[4:5], off
	s_nop 0
	global_load_dwordx4 v[20:23], v[8:9], off
	s_nop 0
	global_load_dwordx4 v[8:11], v[46:47], off
	global_load_dwordx4 v[32:35], v[0:1], off
	v_add_co_u32_e32 v12, vcc, 0x80000, v0
	s_xor_b32 s35, s35, s39
	s_nop 0
	v_addc_co_u32_e32 v13, vcc, 0, v1, vcc
	global_load_dwordx4 v[40:43], v[12:13], off
	s_sub_i32 s35, s35, s39
	s_cmp_gt_i32 s35, 0
	s_cselect_b64 s[42:43], -1, 0
	s_cmp_lt_i32 s35, 1
	s_cbranch_scc1 .LBB0_43
	v_add_co_u32_e32 v12, vcc, 0x80000, v46
	s_nop 1
	v_addc_co_u32_e32 v13, vcc, 0, v47, vcc
	v_add_co_u32_e32 v14, vcc, 0x100000, v46
	s_nop 1
	v_addc_co_u32_e32 v15, vcc, 0, v47, vcc
	global_load_dwordx4 v[16:19], v[12:13], off offset:128
	global_load_dwordx4 v[28:31], v[14:15], off offset:128
	s_nop 0
	global_load_dwordx4 v[12:15], v[46:47], off offset:128
	global_load_dwordx4 v[24:27], v[0:1], off offset:128
	s_waitcnt vmcnt(9)
	v_add_co_u32_e32 v36, vcc, 0x80000, v0
	s_nop 1
	v_addc_co_u32_e32 v37, vcc, 0, v1, vcc
	global_load_dwordx4 v[36:39], v[36:37], off offset:128
	s_branch .LBB0_44

.Lgm_f1_entry:
	s_add_u32 s56, s96, 0x3a24000
	s_addc_u32 s57, s97, 0
	s_mov_b32 s52, s61
	s_mov_b32 s53, s63
	s_movk_i32 s54, 0x400
	s_cmp_ge_u32 s53, s54
	s_cbranch_scc1 .Lgm_f1_exit
	s_mov_b32 s30, 0
	s_mov_b32 s4, s53
.Lgm_f1_cnt:
	s_add_u32 s30, s30, 16
	s_add_u32 s4, s4, s52
	s_cmp_lt_u32 s4, s54
	s_cbranch_scc1 .Lgm_f1_cnt
	s_add_u32 s48, s96, 0x2e24000
	s_addc_u32 s49, s97, 0
	s_mul_i32 s4, s36, 0x800000
	s_add_u32 s50, s96, 0xd80000
	s_addc_u32 s51, s97, 0
	s_add_u32 s50, s50, s4
	s_addc_u32 s51, s51, 0
	v_and_b32_e32 v0, 63, v206
	v_lshrrev_b32_e32 v1, 6, v206
	v_lshrrev_b32_e32 v3, 3, v0
	v_and_b32_e32 v4, 7, v0
	v_readfirstlane_b32 s42, v1
	v_xor_b32_e32 v4, v4, v3
	v_lshl_add_u32 v3, v1, 3, v3
	v_lshlrev_b32_e32 v3, 11, v3
	v_lshl_add_u32 v148, v4, 4, v3
	v_add_u32_e32 v149, 0x20000, v148
	v_add_u32_e32 v150, 0x40000, v148
	v_and_b32_e32 v5, 15, v0
	v_lshrrev_b32_e32 v6, 4, v0
	v_and_b32_e32 v7, 7, v5
	v_xor_b32_e32 v7, v7, v6
	v_lshlrev_b32_e32 v7, 4, v7
	v_lshrrev_b32_e32 v8, 1, v1
	v_and_b32_e32 v9, 1, v1
	v_mul_u32_u24_e32 v10, 48, v8
	v_add_u32_e32 v11, v10, v5
	v_lshl_add_u32 v151, v11, 7, v7
	v_xor_b32_e32 v152, 64, v151
	v_lshl_add_u32 v11, v9, 6, v5
	v_lshl_add_u32 v153, v11, 7, v7
	v_add_u32_e32 v153, 0x6000, v153
	v_xor_b32_e32 v154, 64, v153
	s_mul_i32 s5, s42, 4352
	s_mov_b32 s6, 0x1ec10
	s_cmp_lt_u32 s42, 4
	s_cselect_b32 s6, 0x1e000, s6
	s_add_u32 s5, s5, s6
	v_mul_u32_u24_e32 v11, 1088, v6
	v_lshl_add_u32 v11, v5, 2, v11
	v_add_u32_e32 v155, s5, v11
	v_mul_u32_u24_e32 v11, 272, v6
	v_lshl_add_u32 v11, v5, 4, v11
	v_add_u32_e32 v156, s5, v11
	v_add_u32_e32 v11, v10, v6
	v_lshlrev_b32_e32 v12, 6, v9
	v_lshl_add_u32 v12, v5, 2, v12
	s_mov_b32 s4, 0x2000
	v_mul_lo_u32 v13, v11, s4
	v_lshl_add_u32 v157, v12, 1, v13
	s_lshl_b32 s42, s42, 10
	v_mov_b32_e32 v44, 0
	v_mov_b32_e32 v45, 0
	v_mov_b32_e32 v46, 0
	v_mov_b32_e32 v47, 0
	v_mov_b32_e32 v48, 0
	v_mov_b32_e32 v49, 0
	v_mov_b32_e32 v50, 0
	v_mov_b32_e32 v51, 0
	v_mov_b32_e32 v52, 0
	v_mov_b32_e32 v53, 0
	v_mov_b32_e32 v54, 0
	v_mov_b32_e32 v55, 0
	v_mov_b32_e32 v56, 0
	v_mov_b32_e32 v57, 0
	v_mov_b32_e32 v58, 0
	v_mov_b32_e32 v59, 0
	v_mov_b32_e32 v60, 0
	v_mov_b32_e32 v61, 0
	v_mov_b32_e32 v62, 0
	v_mov_b32_e32 v63, 0
	v_mov_b32_e32 v64, 0
	v_mov_b32_e32 v65, 0
	v_mov_b32_e32 v66, 0
	v_mov_b32_e32 v67, 0
	v_mov_b32_e32 v68, 0
	v_mov_b32_e32 v69, 0
	v_mov_b32_e32 v70, 0
	v_mov_b32_e32 v71, 0
	v_mov_b32_e32 v72, 0
	v_mov_b32_e32 v73, 0
	v_mov_b32_e32 v74, 0
	v_mov_b32_e32 v75, 0
	v_mov_b32_e32 v76, 0
	v_mov_b32_e32 v77, 0
	v_mov_b32_e32 v78, 0
	v_mov_b32_e32 v79, 0
	v_mov_b32_e32 v80, 0
	v_mov_b32_e32 v81, 0
	v_mov_b32_e32 v82, 0
	v_mov_b32_e32 v83, 0
	v_mov_b32_e32 v84, 0
	v_mov_b32_e32 v85, 0
	v_mov_b32_e32 v86, 0
	v_mov_b32_e32 v87, 0
	v_mov_b32_e32 v88, 0
	v_mov_b32_e32 v89, 0
	v_mov_b32_e32 v90, 0
	v_mov_b32_e32 v91, 0
	s_mov_b32 s31, 0
	s_mov_b32 s34, 0
	s_mov_b32 s35, s53
	s_mov_b32 s38, s53
	s_mov_b32 s39, 0
	s_mov_b32 s40, 0
	s_mov_b32 s41, s42
	s_and_b32 s4, s38, 31
	s_mul_i32 s4, s4, 0x60000
	s_add_u32 s44, s48, s4
	s_addc_u32 s45, s49, 0
	s_lshr_b32 s4, s38, 5
	s_mul_i32 s4, s4, 0x40000
	s_add_u32 s46, s50, s4
	s_addc_u32 s47, s51, 0
	s_add_u32 m0, s41, 0x0
	s_nop 0
	global_load_lds_dwordx4 v148, s[44:45]
	s_add_u32 m0, s41, 0x2000
	s_nop 0
	global_load_lds_dwordx4 v149, s[44:45]
	s_add_u32 m0, s41, 0x4000
	s_nop 0
	global_load_lds_dwordx4 v150, s[44:45]
	s_add_u32 m0, s41, 0x6000
	s_nop 0
	global_load_lds_dwordx4 v148, s[46:47]
	s_add_u32 m0, s41, 0x8000
	s_nop 0
	global_load_lds_dwordx4 v149, s[46:47]
	s_add_u32 s39, s39, 1
	s_add_u32 s44, s44, 0x80
	s_addc_u32 s45, s45, 0
	s_add_u32 s46, s46, 0x80
	s_addc_u32 s47, s47, 0
	s_cmp_lt_u32 s39, 16
	s_cbranch_scc1 .Lgm_f1_dadv1
	s_mov_b32 s39, 0
	s_add_u32 s4, s38, s52
	s_cmp_lt_u32 s4, s54
	s_cselect_b32 s38, s4, s38
	s_and_b32 s4, s38, 31
	s_mul_i32 s4, s4, 0x60000
	s_add_u32 s44, s48, s4
	s_addc_u32 s45, s49, 0
	s_lshr_b32 s4, s38, 5
	s_mul_i32 s4, s4, 0x40000
	s_add_u32 s46, s50, s4
	s_addc_u32 s47, s51, 0
.Lgm_f1_dadv1:
	s_add_u32 s41, s41, 0xa000
	s_sub_u32 s4, s41, 0x1e000
	s_cmp_ge_u32 s41, 0x1e000
	s_cselect_b32 s41, s4, s41
	s_add_u32 m0, s41, 0x0
	s_nop 0
	global_load_lds_dwordx4 v148, s[44:45]
	s_add_u32 m0, s41, 0x2000
	s_nop 0
	global_load_lds_dwordx4 v149, s[44:45]
	s_add_u32 m0, s41, 0x4000
	s_nop 0
	global_load_lds_dwordx4 v150, s[44:45]
	s_add_u32 m0, s41, 0x6000
	s_nop 0
	global_load_lds_dwordx4 v148, s[46:47]
	s_add_u32 m0, s41, 0x8000
	s_nop 0
	global_load_lds_dwordx4 v149, s[46:47]
	s_add_u32 s39, s39, 1
	s_add_u32 s44, s44, 0x80
	s_addc_u32 s45, s45, 0
	s_add_u32 s46, s46, 0x80
	s_addc_u32 s47, s47, 0
	s_cmp_lt_u32 s39, 16
	s_cbranch_scc1 .Lgm_f1_dadv2
	s_mov_b32 s39, 0
	s_add_u32 s4, s38, s52
	s_cmp_lt_u32 s4, s54
	s_cselect_b32 s38, s4, s38
	s_and_b32 s4, s38, 31
	s_mul_i32 s4, s4, 0x60000
	s_add_u32 s44, s48, s4
	s_addc_u32 s45, s49, 0
	s_lshr_b32 s4, s38, 5
	s_mul_i32 s4, s4, 0x40000
	s_add_u32 s46, s50, s4
	s_addc_u32 s47, s51, 0
.Lgm_f1_dadv2:
	s_add_u32 s41, s41, 0xa000
	s_sub_u32 s4, s41, 0x1e000
	s_cmp_ge_u32 s41, 0x1e000
	s_cselect_b32 s41, s4, s41
	s_waitcnt vmcnt(5)
.Lgm_f1_loop:
	s_barrier
	ds_read_b128 v[92:95], v151 offset:0
	ds_read_b128 v[96:99], v151 offset:2048
	ds_read_b128 v[100:103], v151 offset:4096
	ds_read_b128 v[104:107], v153 offset:0
	ds_read_b128 v[108:111], v153 offset:2048
	ds_read_b128 v[112:115], v153 offset:4096
	ds_read_b128 v[116:119], v153 offset:6144
	s_cmp_eq_u32 s34, 0
	s_cbranch_scc1 .Lgm_f1_first
	v_mfma_f32_16x16x32_bf16 v[44:47], v[120:123], v[132:135], v[44:47]
	v_mfma_f32_16x16x32_bf16 v[60:63], v[124:127], v[132:135], v[60:63]
	s_add_u32 m0, s41, 0x0
	v_mfma_f32_16x16x32_bf16 v[76:79], v[128:131], v[132:135], v[76:79]
	global_load_lds_dwordx4 v148, s[44:45]
	v_mfma_f32_16x16x32_bf16 v[48:51], v[120:123], v[136:139], v[48:51]
	s_add_u32 m0, s41, 0x2000
	v_mfma_f32_16x16x32_bf16 v[64:67], v[124:127], v[136:139], v[64:67]
	global_load_lds_dwordx4 v149, s[44:45]
	v_mfma_f32_16x16x32_bf16 v[80:83], v[128:131], v[136:139], v[80:83]
	s_add_u32 m0, s41, 0x4000
	v_mfma_f32_16x16x32_bf16 v[52:55], v[120:123], v[140:143], v[52:55]
	global_load_lds_dwordx4 v150, s[44:45]
	v_mfma_f32_16x16x32_bf16 v[68:71], v[124:127], v[140:143], v[68:71]
	s_add_u32 m0, s41, 0x6000
	v_mfma_f32_16x16x32_bf16 v[84:87], v[128:131], v[140:143], v[84:87]
	global_load_lds_dwordx4 v148, s[46:47]
	v_mfma_f32_16x16x32_bf16 v[56:59], v[120:123], v[144:147], v[56:59]
	s_add_u32 m0, s41, 0x8000
	v_mfma_f32_16x16x32_bf16 v[72:75], v[124:127], v[144:147], v[72:75]
	global_load_lds_dwordx4 v149, s[46:47]
	v_mfma_f32_16x16x32_bf16 v[88:91], v[128:131], v[144:147], v[88:91]
	s_branch .Lgm_f1_join
.Lgm_f1_first:
	s_add_u32 m0, s41, 0x0
	s_nop 0
	global_load_lds_dwordx4 v148, s[44:45]
	s_add_u32 m0, s41, 0x2000
	s_nop 0
	global_load_lds_dwordx4 v149, s[44:45]
	s_add_u32 m0, s41, 0x4000
	s_nop 0
	global_load_lds_dwordx4 v150, s[44:45]
	s_add_u32 m0, s41, 0x6000
	s_nop 0
	global_load_lds_dwordx4 v148, s[46:47]
	s_add_u32 m0, s41, 0x8000
	s_nop 0
	global_load_lds_dwordx4 v149, s[46:47]
.Lgm_f1_join:
	s_add_u32 s39, s39, 1
	s_add_u32 s44, s44, 0x80
	s_addc_u32 s45, s45, 0
	s_add_u32 s46, s46, 0x80
	s_addc_u32 s47, s47, 0
	s_cmp_lt_u32 s39, 16
	s_cbranch_scc1 .Lgm_f1_dadv3
	s_mov_b32 s39, 0
	s_add_u32 s4, s38, s52
	s_cmp_lt_u32 s4, s54
	s_cselect_b32 s38, s4, s38
	s_and_b32 s4, s38, 31
	s_mul_i32 s4, s4, 0x60000
	s_add_u32 s44, s48, s4
	s_addc_u32 s45, s49, 0
	s_lshr_b32 s4, s38, 5
	s_mul_i32 s4, s4, 0x40000
	s_add_u32 s46, s50, s4
	s_addc_u32 s47, s51, 0
.Lgm_f1_dadv3:
	ds_read_b128 v[120:123], v152 offset:0
	ds_read_b128 v[124:127], v152 offset:2048
	ds_read_b128 v[128:131], v152 offset:4096
	ds_read_b128 v[132:135], v154 offset:0
	ds_read_b128 v[136:139], v154 offset:2048
	ds_read_b128 v[140:143], v154 offset:4096
	ds_read_b128 v[144:147], v154 offset:6144
	s_waitcnt lgkmcnt(10)
	v_mfma_f32_16x16x32_bf16 v[44:47], v[92:95], v[104:107], v[44:47]
	v_mfma_f32_16x16x32_bf16 v[60:63], v[96:99], v[104:107], v[60:63]
	v_mfma_f32_16x16x32_bf16 v[76:79], v[100:103], v[104:107], v[76:79]
	s_waitcnt lgkmcnt(9)
	v_mfma_f32_16x16x32_bf16 v[48:51], v[92:95], v[108:111], v[48:51]
	v_mfma_f32_16x16x32_bf16 v[64:67], v[96:99], v[108:111], v[64:67]
	v_mfma_f32_16x16x32_bf16 v[80:83], v[100:103], v[108:111], v[80:83]
	s_waitcnt lgkmcnt(8)
	v_mfma_f32_16x16x32_bf16 v[52:55], v[92:95], v[112:115], v[52:55]
	v_mfma_f32_16x16x32_bf16 v[68:71], v[96:99], v[112:115], v[68:71]
	v_mfma_f32_16x16x32_bf16 v[84:87], v[100:103], v[112:115], v[84:87]
	s_waitcnt lgkmcnt(7)
	v_mfma_f32_16x16x32_bf16 v[56:59], v[92:95], v[116:119], v[56:59]
	v_mfma_f32_16x16x32_bf16 v[72:75], v[96:99], v[116:119], v[72:75]
	v_mfma_f32_16x16x32_bf16 v[88:91], v[100:103], v[116:119], v[88:91]
	s_waitcnt lgkmcnt(0)
	s_add_u32 s34, s34, 1
	s_cmp_lt_u32 s34, 16
	s_cbranch_scc1 .Lgm_f1_next
	v_mfma_f32_16x16x32_bf16 v[44:47], v[120:123], v[132:135], v[44:47]
	v_mfma_f32_16x16x32_bf16 v[60:63], v[124:127], v[132:135], v[60:63]
	v_mfma_f32_16x16x32_bf16 v[76:79], v[128:131], v[132:135], v[76:79]
	v_mfma_f32_16x16x32_bf16 v[48:51], v[120:123], v[136:139], v[48:51]
	v_mfma_f32_16x16x32_bf16 v[64:67], v[124:127], v[136:139], v[64:67]
	v_mfma_f32_16x16x32_bf16 v[80:83], v[128:131], v[136:139], v[80:83]
	v_mfma_f32_16x16x32_bf16 v[52:55], v[120:123], v[140:143], v[52:55]
	v_mfma_f32_16x16x32_bf16 v[68:71], v[124:127], v[140:143], v[68:71]
	v_mfma_f32_16x16x32_bf16 v[84:87], v[128:131], v[140:143], v[84:87]
	v_mfma_f32_16x16x32_bf16 v[56:59], v[120:123], v[144:147], v[56:59]
	v_mfma_f32_16x16x32_bf16 v[72:75], v[124:127], v[144:147], v[72:75]
	v_mfma_f32_16x16x32_bf16 v[88:91], v[128:131], v[144:147], v[88:91]
	s_and_b32 s6, s35, 31
	s_mul_i32 s6, s6, 192
	s_lshr_b32 s7, s35, 5
	s_lshl_b32 s7, s7, 7
	s_nop 7
	s_mul_i32 s4, s6, 0x2000
	s_lshl_b32 s5, s7, 1
	s_add_u32 s4, s4, s5
	v_add_u32_e32 v158, s4, v157
	ds_write_b32 v155, v44 offset:0
	ds_write_b32 v155, v45 offset:272
	ds_write_b32 v155, v46 offset:544
	ds_write_b32 v155, v47 offset:816
	ds_write_b32 v155, v48 offset:64
	ds_write_b32 v155, v49 offset:336
	ds_write_b32 v155, v50 offset:608
	ds_write_b32 v155, v51 offset:880
	ds_write_b32 v155, v52 offset:128
	ds_write_b32 v155, v53 offset:400
	ds_write_b32 v155, v54 offset:672
	ds_write_b32 v155, v55 offset:944
	ds_write_b32 v155, v56 offset:192
	ds_write_b32 v155, v57 offset:464
	ds_write_b32 v155, v58 offset:736
	ds_write_b32 v155, v59 offset:1008
	s_waitcnt lgkmcnt(0)
	ds_read_b128 v[16:19], v156 offset:0
	ds_read_b128 v[20:23], v156 offset:1088
	ds_read_b128 v[24:27], v156 offset:2176
	ds_read_b128 v[28:31], v156 offset:3264
	s_waitcnt lgkmcnt(3)
	v_max_f32_e32 v16, 0, v16
	v_max_f32_e32 v17, 0, v17
	v_max_f32_e32 v18, 0, v18
	v_max_f32_e32 v19, 0, v19
	v_mul_f32_e32 v16, v16, v16
	v_mul_f32_e32 v17, v17, v17
	v_mul_f32_e32 v18, v18, v18
	v_mul_f32_e32 v19, v19, v19
	v_cvt_pk_bf16_f32 v32, v16, v17
	v_cvt_pk_bf16_f32 v33, v18, v19
	global_store_dwordx2 v158, v[32:33], s[56:57]
	v_add_u32_e32 v158, 0x8000, v158
	s_waitcnt lgkmcnt(2)
	v_max_f32_e32 v20, 0, v20
	v_max_f32_e32 v21, 0, v21
	v_max_f32_e32 v22, 0, v22
	v_max_f32_e32 v23, 0, v23
	v_mul_f32_e32 v20, v20, v20
	v_mul_f32_e32 v21, v21, v21
	v_mul_f32_e32 v22, v22, v22
	v_mul_f32_e32 v23, v23, v23
	v_cvt_pk_bf16_f32 v34, v20, v21
	v_cvt_pk_bf16_f32 v35, v22, v23
	global_store_dwordx2 v158, v[34:35], s[56:57]
	v_add_u32_e32 v158, 0x8000, v158
	s_waitcnt lgkmcnt(1)
	v_max_f32_e32 v24, 0, v24
	v_max_f32_e32 v25, 0, v25
	v_max_f32_e32 v26, 0, v26
	v_max_f32_e32 v27, 0, v27
	v_mul_f32_e32 v24, v24, v24
	v_mul_f32_e32 v25, v25, v25
	v_mul_f32_e32 v26, v26, v26
	v_mul_f32_e32 v27, v27, v27
	v_cvt_pk_bf16_f32 v36, v24, v25
	v_cvt_pk_bf16_f32 v37, v26, v27
	global_store_dwordx2 v158, v[36:37], s[56:57]
	v_add_u32_e32 v158, 0x8000, v158
	s_waitcnt lgkmcnt(0)
	v_max_f32_e32 v28, 0, v28
	v_max_f32_e32 v29, 0, v29
	v_max_f32_e32 v30, 0, v30
	v_max_f32_e32 v31, 0, v31
	v_mul_f32_e32 v28, v28, v28
	v_mul_f32_e32 v29, v29, v29
	v_mul_f32_e32 v30, v30, v30
	v_mul_f32_e32 v31, v31, v31
	v_cvt_pk_bf16_f32 v38, v28, v29
	v_cvt_pk_bf16_f32 v39, v30, v31
	global_store_dwordx2 v158, v[38:39], s[56:57]
	v_add_u32_e32 v158, 0x8000, v158
	ds_write_b32 v155, v60 offset:0
	ds_write_b32 v155, v61 offset:272
	ds_write_b32 v155, v62 offset:544
	ds_write_b32 v155, v63 offset:816
	ds_write_b32 v155, v64 offset:64
	ds_write_b32 v155, v65 offset:336
	ds_write_b32 v155, v66 offset:608
	ds_write_b32 v155, v67 offset:880
	ds_write_b32 v155, v68 offset:128
	ds_write_b32 v155, v69 offset:400
	ds_write_b32 v155, v70 offset:672
	ds_write_b32 v155, v71 offset:944
	ds_write_b32 v155, v72 offset:192
	ds_write_b32 v155, v73 offset:464
	ds_write_b32 v155, v74 offset:736
	ds_write_b32 v155, v75 offset:1008
	s_waitcnt lgkmcnt(0)
	ds_read_b128 v[16:19], v156 offset:0
	ds_read_b128 v[20:23], v156 offset:1088
	ds_read_b128 v[24:27], v156 offset:2176
	ds_read_b128 v[28:31], v156 offset:3264
	s_waitcnt lgkmcnt(3)
	v_max_f32_e32 v16, 0, v16
	v_max_f32_e32 v17, 0, v17
	v_max_f32_e32 v18, 0, v18
	v_max_f32_e32 v19, 0, v19
	v_mul_f32_e32 v16, v16, v16
	v_mul_f32_e32 v17, v17, v17
	v_mul_f32_e32 v18, v18, v18
	v_mul_f32_e32 v19, v19, v19
	v_cvt_pk_bf16_f32 v32, v16, v17
	v_cvt_pk_bf16_f32 v33, v18, v19
	global_store_dwordx2 v158, v[32:33], s[56:57]
	v_add_u32_e32 v158, 0x8000, v158
	s_waitcnt lgkmcnt(2)
	v_max_f32_e32 v20, 0, v20
	v_max_f32_e32 v21, 0, v21
	v_max_f32_e32 v22, 0, v22
	v_max_f32_e32 v23, 0, v23
	v_mul_f32_e32 v20, v20, v20
	v_mul_f32_e32 v21, v21, v21
	v_mul_f32_e32 v22, v22, v22
	v_mul_f32_e32 v23, v23, v23
	v_cvt_pk_bf16_f32 v34, v20, v21
	v_cvt_pk_bf16_f32 v35, v22, v23
	global_store_dwordx2 v158, v[34:35], s[56:57]
	v_add_u32_e32 v158, 0x8000, v158
	s_waitcnt lgkmcnt(1)
	v_max_f32_e32 v24, 0, v24
	v_max_f32_e32 v25, 0, v25
	v_max_f32_e32 v26, 0, v26
	v_max_f32_e32 v27, 0, v27
	v_mul_f32_e32 v24, v24, v24
	v_mul_f32_e32 v25, v25, v25
	v_mul_f32_e32 v26, v26, v26
	v_mul_f32_e32 v27, v27, v27
	v_cvt_pk_bf16_f32 v36, v24, v25
	v_cvt_pk_bf16_f32 v37, v26, v27
	global_store_dwordx2 v158, v[36:37], s[56:57]
	v_add_u32_e32 v158, 0x8000, v158
	s_waitcnt lgkmcnt(0)
	v_max_f32_e32 v28, 0, v28
	v_max_f32_e32 v29, 0, v29
	v_max_f32_e32 v30, 0, v30
	v_max_f32_e32 v31, 0, v31
	v_mul_f32_e32 v28, v28, v28
	v_mul_f32_e32 v29, v29, v29
	v_mul_f32_e32 v30, v30, v30
	v_mul_f32_e32 v31, v31, v31
	v_cvt_pk_bf16_f32 v38, v28, v29
	v_cvt_pk_bf16_f32 v39, v30, v31
	global_store_dwordx2 v158, v[38:39], s[56:57]
	v_add_u32_e32 v158, 0x8000, v158
	ds_write_b32 v155, v76 offset:0
	ds_write_b32 v155, v77 offset:272
	ds_write_b32 v155, v78 offset:544
	ds_write_b32 v155, v79 offset:816
	ds_write_b32 v155, v80 offset:64
	ds_write_b32 v155, v81 offset:336
	ds_write_b32 v155, v82 offset:608
	ds_write_b32 v155, v83 offset:880
	ds_write_b32 v155, v84 offset:128
	ds_write_b32 v155, v85 offset:400
	ds_write_b32 v155, v86 offset:672
	ds_write_b32 v155, v87 offset:944
	ds_write_b32 v155, v88 offset:192
	ds_write_b32 v155, v89 offset:464
	ds_write_b32 v155, v90 offset:736
	ds_write_b32 v155, v91 offset:1008
	s_waitcnt lgkmcnt(0)
	ds_read_b128 v[16:19], v156 offset:0
	ds_read_b128 v[20:23], v156 offset:1088
	ds_read_b128 v[24:27], v156 offset:2176
	ds_read_b128 v[28:31], v156 offset:3264
	s_waitcnt lgkmcnt(3)
	v_max_f32_e32 v16, 0, v16
	v_max_f32_e32 v17, 0, v17
	v_max_f32_e32 v18, 0, v18
	v_max_f32_e32 v19, 0, v19
	v_mul_f32_e32 v16, v16, v16
	v_mul_f32_e32 v17, v17, v17
	v_mul_f32_e32 v18, v18, v18
	v_mul_f32_e32 v19, v19, v19
	v_cvt_pk_bf16_f32 v32, v16, v17
	v_cvt_pk_bf16_f32 v33, v18, v19
	global_store_dwordx2 v158, v[32:33], s[56:57]
	v_add_u32_e32 v158, 0x8000, v158
	s_waitcnt lgkmcnt(2)
	v_max_f32_e32 v20, 0, v20
	v_max_f32_e32 v21, 0, v21
	v_max_f32_e32 v22, 0, v22
	v_max_f32_e32 v23, 0, v23
	v_mul_f32_e32 v20, v20, v20
	v_mul_f32_e32 v21, v21, v21
	v_mul_f32_e32 v22, v22, v22
	v_mul_f32_e32 v23, v23, v23
	v_cvt_pk_bf16_f32 v34, v20, v21
	v_cvt_pk_bf16_f32 v35, v22, v23
	global_store_dwordx2 v158, v[34:35], s[56:57]
	v_add_u32_e32 v158, 0x8000, v158
	s_waitcnt lgkmcnt(1)
	v_max_f32_e32 v24, 0, v24
	v_max_f32_e32 v25, 0, v25
	v_max_f32_e32 v26, 0, v26
	v_max_f32_e32 v27, 0, v27
	v_mul_f32_e32 v24, v24, v24
	v_mul_f32_e32 v25, v25, v25
	v_mul_f32_e32 v26, v26, v26
	v_mul_f32_e32 v27, v27, v27
	v_cvt_pk_bf16_f32 v36, v24, v25
	v_cvt_pk_bf16_f32 v37, v26, v27
	global_store_dwordx2 v158, v[36:37], s[56:57]
	v_add_u32_e32 v158, 0x8000, v158
	s_waitcnt lgkmcnt(0)
	v_max_f32_e32 v28, 0, v28
	v_max_f32_e32 v29, 0, v29
	v_max_f32_e32 v30, 0, v30
	v_max_f32_e32 v31, 0, v31
	v_mul_f32_e32 v28, v28, v28
	v_mul_f32_e32 v29, v29, v29
	v_mul_f32_e32 v30, v30, v30
	v_mul_f32_e32 v31, v31, v31
	v_cvt_pk_bf16_f32 v38, v28, v29
	v_cvt_pk_bf16_f32 v39, v30, v31
	global_store_dwordx2 v158, v[38:39], s[56:57]
	v_add_u32_e32 v158, 0x8000, v158
	v_mov_b32_e32 v44, 0
	v_mov_b32_e32 v45, 0
	v_mov_b32_e32 v46, 0
	v_mov_b32_e32 v47, 0
	v_mov_b32_e32 v48, 0
	v_mov_b32_e32 v49, 0
	v_mov_b32_e32 v50, 0
	v_mov_b32_e32 v51, 0
	v_mov_b32_e32 v52, 0
	v_mov_b32_e32 v53, 0
	v_mov_b32_e32 v54, 0
	v_mov_b32_e32 v55, 0
	v_mov_b32_e32 v56, 0
	v_mov_b32_e32 v57, 0
	v_mov_b32_e32 v58, 0
	v_mov_b32_e32 v59, 0
	v_mov_b32_e32 v60, 0
	v_mov_b32_e32 v61, 0
	v_mov_b32_e32 v62, 0
	v_mov_b32_e32 v63, 0
	v_mov_b32_e32 v64, 0
	v_mov_b32_e32 v65, 0
	v_mov_b32_e32 v66, 0
	v_mov_b32_e32 v67, 0
	v_mov_b32_e32 v68, 0
	v_mov_b32_e32 v69, 0
	v_mov_b32_e32 v70, 0
	v_mov_b32_e32 v71, 0
	v_mov_b32_e32 v72, 0
	v_mov_b32_e32 v73, 0
	v_mov_b32_e32 v74, 0
	v_mov_b32_e32 v75, 0
	v_mov_b32_e32 v76, 0
	v_mov_b32_e32 v77, 0
	v_mov_b32_e32 v78, 0
	v_mov_b32_e32 v79, 0
	v_mov_b32_e32 v80, 0
	v_mov_b32_e32 v81, 0
	v_mov_b32_e32 v82, 0
	v_mov_b32_e32 v83, 0
	v_mov_b32_e32 v84, 0
	v_mov_b32_e32 v85, 0
	v_mov_b32_e32 v86, 0
	v_mov_b32_e32 v87, 0
	v_mov_b32_e32 v88, 0
	v_mov_b32_e32 v89, 0
	v_mov_b32_e32 v90, 0
	v_mov_b32_e32 v91, 0
	s_mov_b32 s34, 0
	s_add_u32 s35, s35, s52
	s_add_u32 s31, s31, 1
	s_cmp_ge_u32 s31, s30
	s_cbranch_scc1 .Lgm_f1_exit
	s_waitcnt vmcnt(17)
	s_branch .Lgm_f1_rot
.Lgm_f1_next:
	s_add_u32 s31, s31, 1
	s_waitcnt vmcnt(5)
.Lgm_f1_rot:
	s_add_u32 s40, s40, 0xa000
	s_mov_b32 s4, 0xa000
	s_cmp_ge_u32 s40, 0x1e000
	s_cselect_b32 s4, 0xfffec000, s4
	s_cselect_b32 s40, 0, s40
	s_add_u32 s41, s41, 0xa000
	s_sub_u32 s5, s41, 0x1e000
	s_cmp_ge_u32 s41, 0x1e000
	s_cselect_b32 s41, s5, s41
	v_add_u32_e32 v151, s4, v151
	v_add_u32_e32 v152, s4, v152
	v_add_u32_e32 v153, s4, v153
	v_add_u32_e32 v154, s4, v154
	s_branch .Lgm_f1_loop
.Lgm_f1_exit:
	s_waitcnt vmcnt(0) lgkmcnt(0)
	s_branch .LBB0_854

.LBB0_158:
	s_andn2_b64 vcc, exec, s[38:39]
	s_cbranch_vccnz .LBB0_181
	s_branch .LBB0_181

	.amdhsa_kernel _Z4mega1Piii
		.amdhsa_group_segment_fixed_size 160784
		.amdhsa_private_segment_fixed_size 0
		.amdhsa_kernarg_size 568
		.amdhsa_user_sgpr_count 2
		.amdhsa_user_sgpr_dispatch_ptr 0
		.amdhsa_user_sgpr_queue_ptr 0
		.amdhsa_user_sgpr_kernarg_segment_ptr 1
		.amdhsa_user_sgpr_dispatch_id 0
		.amdhsa_user_sgpr_kernarg_preload_length 0
		.amdhsa_user_sgpr_kernarg_preload_offset 0
		.amdhsa_user_sgpr_private_segment_size 0
		.amdhsa_uses_dynamic_stack 0
		.amdhsa_enable_private_segment 0
		.amdhsa_system_sgpr_workgroup_id_x 1
		.amdhsa_system_sgpr_workgroup_id_y 0
		.amdhsa_system_sgpr_workgroup_id_z 0
		.amdhsa_system_sgpr_workgroup_info 0
		.amdhsa_system_vgpr_workitem_id 2
		.amdhsa_next_free_vgpr 238
		.amdhsa_next_free_sgpr 102
		.amdhsa_accum_offset 240
		.amdhsa_reserve_vcc 1
		.amdhsa_float_round_mode_32 0
		.amdhsa_float_round_mode_16_64 0
		.amdhsa_float_denorm_mode_32 3
		.amdhsa_float_denorm_mode_16_64 3
		.amdhsa_dx10_clamp 1
		.amdhsa_ieee_mode 1
		.amdhsa_fp16_overflow 0
		.amdhsa_tg_split 0
		.amdhsa_exception_fp_ieee_invalid_op 0
		.amdhsa_exception_fp_denorm_src 0
		.amdhsa_exception_fp_ieee_div_zero 0
		.amdhsa_exception_fp_ieee_overflow 0
		.amdhsa_exception_fp_ieee_underflow 0
		.amdhsa_exception_fp_ieee_inexact 0
		.amdhsa_exception_int_div_zero 0
	.end_amdhsa_kernel

amdhsa.kernels:
  - .agpr_count:     0
    .args:
      - .offset:         0
        .size:           296
        .value_kind:     by_value
      - .offset:         296
        .size:           4
        .value_kind:     by_value
      - .offset:         300
        .size:           4
        .value_kind:     by_value
      - .offset:         304
        .size:           4
        .value_kind:     by_value
      - .offset:         312
        .size:           4
        .value_kind:     hidden_block_count_x
      - .offset:         316
        .size:           4
        .value_kind:     hidden_block_count_y
      - .offset:         320
        .size:           4
        .value_kind:     hidden_block_count_z
      - .offset:         324
        .size:           2
        .value_kind:     hidden_group_size_x
      - .offset:         326
        .size:           2
        .value_kind:     hidden_group_size_y
      - .offset:         328
        .size:           2
        .value_kind:     hidden_group_size_z
      - .offset:         330
        .size:           2
        .value_kind:     hidden_remainder_x
      - .offset:         332
        .size:           2
        .value_kind:     hidden_remainder_y
      - .offset:         334
        .size:           2
        .value_kind:     hidden_remainder_z
      - .offset:         352
        .size:           8
        .value_kind:     hidden_global_offset_x
      - .offset:         360
        .size:           8
        .value_kind:     hidden_global_offset_y
      - .offset:         368
        .size:           8
        .value_kind:     hidden_global_offset_z
      - .offset:         376
        .size:           2
        .value_kind:     hidden_grid_dims
      - .offset:         400
        .size:           8
        .value_kind:     hidden_multigrid_sync_arg
    .group_segment_fixed_size: 160784
    .kernarg_segment_align: 8
    .kernarg_segment_size: 568
    .language:       OpenCL C
    .language_version:
      - 2
      - 0
    .max_flat_workgroup_size: 512
    .name:           _Z4mega1Piii
    .private_segment_fixed_size: 0
    .sgpr_count:     108
    .sgpr_spill_count: 197
    .symbol:         _Z4mega1Piii.kd
    .uniform_work_group_size: 1
    .uses_dynamic_stack: false
    .vgpr_count:     238
    .vgpr_spill_count: 0
    .wavefront_size: 64
